# same straight-line residual epilogue for the WO (mixer out) full-mask units; on top of v039
# speedup vs baseline: 1.0092x; 1.0092x over previous
.Ltramp_gbar:
	s_branch .LBB0_1633
.Ltramp_772:
	s_branch .LBB0_772

.LBB0_1109:
	s_and_b64 vcc, exec, s[14:15]
	s_cbranch_vccz .LBB0_1172
	s_add_u32 s16, s12, 0x1aa00000
	s_mul_i32 s0, s36, 3
	s_mul_i32 s6, s36, 0x36000
	s_addc_u32 s17, s13, 0
	s_add_i32 s1, s0, 1
	s_add_i32 s7, s6, 0x12000
	s_mul_hi_i32 s1, s1, 0x12000
	s_add_u32 s7, s12, s7
	s_addc_u32 s1, s13, s1
	s_add_u32 s14, s7, 0x20000
	v_readlane_b32 s7, v254, 44
	s_addc_u32 s15, s1, 0
	s_mul_hi_i32 s0, s0, 0x12000
	v_mov_b32_e32 v2, s7
	ds_read_b32 v2, v2
	s_add_u32 s1, s12, s6
	v_readlane_b32 s7, v254, 45
	s_addc_u32 s6, s13, s0
	s_add_u32 s0, s1, 0x20000
	s_waitcnt lgkmcnt(0)
	v_mov_b32_e32 v4, s7
	v_readlane_b32 s7, v254, 46
	s_addc_u32 s1, s6, 0
	v_readlane_b32 s6, v254, 38
	v_mov_b32_e32 v5, s7
	v_readlane_b32 s7, v254, 47
	v_readfirstlane_b32 s28, v2
	v_mov_b32_e32 v2, s6
	s_waitcnt vmcnt(0)
	v_mov_b32_e32 v134, s7
	ds_read_b32 v4, v4
	ds_read_b32 v5, v5
	ds_read_b32 v134, v134
	ds_read_b32 v2, v2
	v_readlane_b32 s6, v254, 39
	s_waitcnt lgkmcnt(3)
	v_readfirstlane_b32 s29, v4
	s_waitcnt lgkmcnt(2)
	v_readfirstlane_b32 s42, v5
	s_waitcnt lgkmcnt(0)
	v_mov_b32_e32 v2, s6
	ds_read_b32 v2, v2
	v_readlane_b32 s6, v254, 40
	v_readfirstlane_b32 s43, v134
	s_cmp_eq_u64 s[0:1], 0
	s_waitcnt lgkmcnt(0)
	v_mov_b32_e32 v2, s6
	ds_read_b32 v2, v2
	v_readlane_b32 s6, v254, 41
	s_waitcnt lgkmcnt(0)
	s_nop 0
	v_mov_b32_e32 v2, s6
	ds_read_b32 v2, v2
	v_readlane_b32 s6, v255, 18
	s_waitcnt lgkmcnt(0)
	v_lshl_add_u32 v2, v191, 3, s70
	v_lshl_add_u32 v178, s3, 8, v2
	v_add_u32_e32 v4, s6, v189
	v_lshl_add_u32 v180, s4, 8, v4
	v_ashrrev_i32_e32 v179, 31, v178
	v_ashrrev_i32_e32 v181, 31, v180
	s_cbranch_scc1 .LBB0_1113
	s_cmp_eq_u32 s84, 0xff
	s_cbranch_scc1 .Lrfast_wo
	v_lshlrev_b64 v[138:139], 12, v[180:181]
	s_mov_b64 s[0:1], 0x10000
	v_lshl_add_u64 v[212:213], v[138:139], 0, s[0:1]
	s_mov_b64 s[0:1], 0x20000
	v_lshl_add_u64 v[210:211], v[138:139], 0, s[0:1]
	s_mov_b64 s[0:1], 0x30000
	v_lshl_add_u64 v[184:185], v[178:179], 1, s[16:17]
	v_lshl_add_u64 v[208:209], v[138:139], 0, s[0:1]
	v_lshl_add_u64 v[204:205], v[184:185], 0, v[212:213]
	v_lshl_add_u64 v[182:183], v[184:185], 0, v[208:209]
	v_lshl_add_u64 v[186:187], v[184:185], 0, v[210:211]
	global_load_dwordx4 v[170:173], v[204:205], off
	global_load_dwordx4 v[166:169], v[186:187], off
	global_load_dwordx4 v[158:161], v[182:183], off
	v_lshlrev_b32_e32 v4, 3, v4
	v_add_u32_e32 v216, 0, v4
	v_add_u32_e32 v4, 0x20000, v216
	ds_read2_b64 v[174:177], v4 offset1:16
	v_lshl_add_u32 v2, v2, 2, 0
	v_add_u32_e32 v197, 0x20800, v2
	v_add_u32_e32 v199, 0x20c00, v2
	ds_read2_b64 v[162:165], v4 offset0:32 offset1:48
	s_waitcnt lgkmcnt(1)
	v_mul_f32_e32 v201, 0x3a000000, v174
	v_mul_f32_e32 v5, v201, v201
	v_fma_f32 v5, v175, s72, -v5
	v_add_f32_e32 v5, 0x3727c5ac, v5
	ds_read_b128 v[150:153], v197
	ds_read_b128 v[142:145], v197 offset:16
	ds_read_b128 v[154:157], v199
	ds_read_b128 v[146:149], v199 offset:16
	v_rsq_f32_e32 v206, v5
	s_and_b32 s6, s84, 1
	s_bitcmp1_b32 s84, 0
	s_cselect_b64 s[0:1], -1, 0
	s_cmp_eq_u32 s6, 0
	v_lshl_add_u64 v[174:175], v[184:185], 0, v[138:139]
	s_cbranch_scc1 .LBB0_1114
	global_load_dwordx4 v[134:137], v[174:175], off
	v_lshl_add_u64 v[138:139], s[16:17], 0, v[138:139]
	v_lshl_add_u64 v[138:139], v[178:179], 1, v[138:139]
	s_waitcnt vmcnt(0)
	v_lshlrev_b32_e32 v2, 16, v134
	v_and_b32_e32 v134, 0xffff0000, v134
	v_lshlrev_b32_e32 v4, 16, v135
	v_and_b32_e32 v5, 0xffff0000, v135
	v_lshlrev_b32_e32 v207, 16, v137
	v_sub_f32_e32 v5, v5, v201
	v_sub_f32_e32 v4, v4, v201
	v_sub_f32_e32 v135, v134, v201
	v_sub_f32_e32 v134, v2, v201
	v_pk_mul_f32 v[134:135], v[206:207], v[134:135] op_sel_hi:[0,1]
	v_pk_mul_f32 v[4:5], v[206:207], v[4:5] op_sel_hi:[0,1]
	v_lshlrev_b32_e32 v203, 16, v136
	v_and_b32_e32 v136, 0xffff0000, v136
	v_and_b32_e32 v137, 0xffff0000, v137
	s_waitcnt lgkmcnt(1)
	v_pk_fma_f32 v[4:5], v[152:153], v[4:5], v[156:157]
	v_pk_fma_f32 v[134:135], v[150:151], v[134:135], v[154:155]
	v_pk_fma_f32 v[214:215], v[4:5], s[76:77], v[128:129] op_sel_hi:[1,0,1]
	v_pk_fma_f32 v[140:141], v[134:135], s[76:77], v[126:127] op_sel_hi:[1,0,1]
	v_sub_f32_e32 v5, v137, v201
	v_sub_f32_e32 v4, v207, v201
	v_sub_f32_e32 v135, v136, v201
	v_sub_f32_e32 v134, v203, v201
	v_pk_mul_f32 v[134:135], v[206:207], v[134:135] op_sel_hi:[0,1]
	v_pk_mul_f32 v[4:5], v[206:207], v[4:5] op_sel_hi:[0,1]
	s_waitcnt lgkmcnt(0)
	v_pk_fma_f32 v[4:5], v[144:145], v[4:5], v[148:149]
	v_pk_fma_f32 v[134:135], v[142:143], v[134:135], v[146:147]
	v_pk_fma_f32 v[222:223], v[4:5], s[76:77], v[132:133] op_sel_hi:[1,0,1]
	v_pk_fma_f32 v[218:219], v[134:135], s[76:77], v[130:131] op_sel_hi:[1,0,1]
	v_pk_add_f32 v[4:5], v[214:215], v[222:223]
	v_pk_add_f32 v[134:135], v[140:141], v[218:219]
	v_pk_mul_f32 v[136:137], v[218:219], v[218:219]
	v_pk_mul_f32 v[224:225], v[222:223], v[222:223]
	v_pk_fma_f32 v[136:137], v[140:141], v[140:141], v[136:137]
	v_pk_fma_f32 v[224:225], v[214:215], v[214:215], v[224:225]
	v_pk_mov_b32 v[226:227], v[134:135], v[4:5] op_sel:[1,0]
	v_mov_b32_e32 v135, v5
	v_pk_add_f32 v[4:5], v[226:227], v[134:135]
	v_pk_mov_b32 v[134:135], v[136:137], v[224:225] op_sel:[1,0]
	v_mov_b32_e32 v137, v225
	v_pk_add_f32 v[134:135], v[134:135], v[136:137]
	v_add_f32_e32 v2, v4, v5
	v_pk_add_f32 v[134:135], v[134:135], v[134:135] op_sel:[0,1] op_sel_hi:[1,0]
	v_add_f32_e32 v2, 0, v2
	v_mov_b32_e32 v4, v3
	v_mov_b32_e32 v5, v3
	v_mov_b32_e32 v135, v3
	v_mov_b32_e32 v136, v3
	v_mov_b32_e32 v137, v3
	v_cvt_pk_bf16_f32 v224, v140, v141
	v_cvt_pk_bf16_f32 v225, v214, v215
	v_cvt_pk_bf16_f32 v226, v218, v219
	v_cvt_pk_bf16_f32 v227, v222, v223
	global_store_dwordx4 v[138:139], v[224:227], off
	s_branch .LBB0_1115

.Lrfast_wo:
	v_lshlrev_b32_e32 v134, 12, v180
	v_lshl_add_u32 v134, v178, 1, v134
	v_add_u32_e32 v135, 0x80000, v134
	v_lshl_add_u32 v138, v191, 4, v180
	v_lshlrev_b32_e32 v138, 3, v138
	s_add_u32 s6, s16, 0x10000
	s_addc_u32 s7, s17, 0
	s_add_u32 s8, s16, 0x20000
	s_addc_u32 s9, s17, 0
	s_add_u32 s10, s16, 0x30000
	s_addc_u32 s11, s17, 0
	v_lshlrev_b32_e32 v136, 3, v4
	v_add_u32_e32 v136, 0x20000, v136
	v_lshlrev_b32_e32 v137, 2, v2
	v_add_u32_e32 v137, 0x20800, v137
	global_load_dwordx4 v[204:207], v134, s[16:17]
	global_load_dwordx4 v[208:211], v134, s[6:7]
	global_load_dwordx4 v[212:215], v134, s[8:9]
	global_load_dwordx4 v[216:219], v134, s[10:11]
	global_load_dwordx4 v[222:225], v134, s[16:17] offset:256
	global_load_dwordx4 v[182:185], v134, s[6:7] offset:256
	global_load_dwordx4 v[166:169], v134, s[8:9] offset:256
	global_load_dwordx4 v[170:173], v134, s[10:11] offset:256
	ds_read2_b64 v[142:145], v136 offset0:0 offset1:16
	ds_read2_b64 v[146:149], v136 offset0:32 offset1:48
	ds_read_b128 v[150:153], v137
	ds_read_b128 v[154:157], v137 offset:16
	ds_read_b128 v[158:161], v137 offset:1024
	ds_read_b128 v[162:165], v137 offset:1040
	v_cmp_lt_i32_e32 vcc, v234, v230
	s_nop 1
	v_cndmask_b32_e32 v201, v228, v234, vcc
	v_cmp_lt_i32_e32 vcc, v195, v230
	s_nop 1
	v_cndmask_b32_e32 v203, v228, v195, vcc
	v_lshlrev_b32_e32 v201, 2, v201
	v_lshlrev_b32_e32 v203, 2, v203
	s_waitcnt lgkmcnt(0)
	v_mul_f32_e32 v142, 0x3a000000, v142
	v_mul_f32_e32 v174, v142, v142
	v_fma_f32 v174, v143, s72, -v174
	v_add_f32_e32 v174, 0x3727c5ac, v174
	v_mul_f32_e32 v144, 0x3a000000, v144
	v_mul_f32_e32 v175, v144, v144
	v_fma_f32 v175, v145, s72, -v175
	v_add_f32_e32 v175, 0x3727c5ac, v175
	v_mul_f32_e32 v146, 0x3a000000, v146
	v_mul_f32_e32 v176, v146, v146
	v_fma_f32 v176, v147, s72, -v176
	v_add_f32_e32 v176, 0x3727c5ac, v176
	v_mul_f32_e32 v148, 0x3a000000, v148
	v_mul_f32_e32 v177, v148, v148
	v_fma_f32 v177, v149, s72, -v177
	v_add_f32_e32 v177, 0x3727c5ac, v177
	v_rsq_f32_e32 v143, v174
	v_rsq_f32_e32 v145, v175
	v_rsq_f32_e32 v147, v176
	v_rsq_f32_e32 v149, v177
	s_nop 0
	s_waitcnt vmcnt(4)
	v_lshlrev_b32_e32 v174, 16, v204
	v_and_b32_e32 v175, 0xffff0000, v204
	v_lshlrev_b32_e32 v176, 16, v205
	v_and_b32_e32 v177, 0xffff0000, v205
	v_lshlrev_b32_e32 v178, 16, v206
	v_and_b32_e32 v179, 0xffff0000, v206
	v_lshlrev_b32_e32 v180, 16, v207
	v_and_b32_e32 v181, 0xffff0000, v207
	v_pk_add_f32 v[174:175], v[174:175], v[142:143] op_sel_hi:[1,0] neg_lo:[0,1] neg_hi:[0,1]
	v_pk_add_f32 v[176:177], v[176:177], v[142:143] op_sel_hi:[1,0] neg_lo:[0,1] neg_hi:[0,1]
	v_pk_add_f32 v[178:179], v[178:179], v[142:143] op_sel_hi:[1,0] neg_lo:[0,1] neg_hi:[0,1]
	v_pk_add_f32 v[180:181], v[180:181], v[142:143] op_sel_hi:[1,0] neg_lo:[0,1] neg_hi:[0,1]
	v_pk_mul_f32 v[174:175], v[142:143], v[174:175] op_sel:[1,0] op_sel_hi:[1,1]
	v_pk_mul_f32 v[176:177], v[142:143], v[176:177] op_sel:[1,0] op_sel_hi:[1,1]
	v_pk_mul_f32 v[178:179], v[142:143], v[178:179] op_sel:[1,0] op_sel_hi:[1,1]
	v_pk_mul_f32 v[180:181], v[142:143], v[180:181] op_sel:[1,0] op_sel_hi:[1,1]
	v_pk_fma_f32 v[174:175], v[150:151], v[174:175], v[158:159]
	v_pk_fma_f32 v[176:177], v[152:153], v[176:177], v[160:161]
	v_pk_fma_f32 v[178:179], v[154:155], v[178:179], v[162:163]
	v_pk_fma_f32 v[180:181], v[156:157], v[180:181], v[164:165]
	v_pk_fma_f32 v[126:127], v[174:175], s[76:77], v[126:127] op_sel_hi:[1,0,1]
	v_pk_fma_f32 v[128:129], v[176:177], s[76:77], v[128:129] op_sel_hi:[1,0,1]
	v_pk_fma_f32 v[130:131], v[178:179], s[76:77], v[130:131] op_sel_hi:[1,0,1]
	v_pk_fma_f32 v[132:133], v[180:181], s[76:77], v[132:133] op_sel_hi:[1,0,1]
	v_pk_add_f32 v[174:175], v[126:127], v[130:131]
	v_pk_add_f32 v[176:177], v[128:129], v[132:133]
	v_pk_mul_f32 v[178:179], v[126:127], v[126:127]
	v_pk_mul_f32 v[180:181], v[128:129], v[128:129]
	v_pk_fma_f32 v[178:179], v[130:131], v[130:131], v[178:179]
	v_pk_fma_f32 v[180:181], v[132:133], v[132:133], v[180:181]
	v_pk_add_f32 v[174:175], v[174:175], v[176:177]
	v_pk_add_f32 v[178:179], v[178:179], v[180:181]
	v_cvt_pk_bf16_f32 v204, v126, v127
	v_cvt_pk_bf16_f32 v205, v128, v129
	v_cvt_pk_bf16_f32 v206, v130, v131
	v_cvt_pk_bf16_f32 v207, v132, v133
	v_add_f32_e32 v2, v174, v175
	v_add_f32_e32 v140, v178, v179
	v_lshlrev_b32_e32 v174, 16, v208
	v_and_b32_e32 v175, 0xffff0000, v208
	v_lshlrev_b32_e32 v176, 16, v209
	v_and_b32_e32 v177, 0xffff0000, v209
	v_lshlrev_b32_e32 v178, 16, v210
	v_and_b32_e32 v179, 0xffff0000, v210
	v_lshlrev_b32_e32 v180, 16, v211
	v_and_b32_e32 v181, 0xffff0000, v211
	v_pk_add_f32 v[174:175], v[174:175], v[144:145] op_sel_hi:[1,0] neg_lo:[0,1] neg_hi:[0,1]
	v_pk_add_f32 v[176:177], v[176:177], v[144:145] op_sel_hi:[1,0] neg_lo:[0,1] neg_hi:[0,1]
	v_pk_add_f32 v[178:179], v[178:179], v[144:145] op_sel_hi:[1,0] neg_lo:[0,1] neg_hi:[0,1]
	v_pk_add_f32 v[180:181], v[180:181], v[144:145] op_sel_hi:[1,0] neg_lo:[0,1] neg_hi:[0,1]
	v_pk_mul_f32 v[174:175], v[144:145], v[174:175] op_sel:[1,0] op_sel_hi:[1,1]
	v_pk_mul_f32 v[176:177], v[144:145], v[176:177] op_sel:[1,0] op_sel_hi:[1,1]
	v_pk_mul_f32 v[178:179], v[144:145], v[178:179] op_sel:[1,0] op_sel_hi:[1,1]
	v_pk_mul_f32 v[180:181], v[144:145], v[180:181] op_sel:[1,0] op_sel_hi:[1,1]
	v_pk_fma_f32 v[174:175], v[150:151], v[174:175], v[158:159]
	v_pk_fma_f32 v[176:177], v[152:153], v[176:177], v[160:161]
	v_pk_fma_f32 v[178:179], v[154:155], v[178:179], v[162:163]
	v_pk_fma_f32 v[180:181], v[156:157], v[180:181], v[164:165]
	v_pk_fma_f32 v[118:119], v[174:175], s[76:77], v[118:119] op_sel_hi:[1,0,1]
	v_pk_fma_f32 v[120:121], v[176:177], s[76:77], v[120:121] op_sel_hi:[1,0,1]
	v_pk_fma_f32 v[122:123], v[178:179], s[76:77], v[122:123] op_sel_hi:[1,0,1]
	v_pk_fma_f32 v[124:125], v[180:181], s[76:77], v[124:125] op_sel_hi:[1,0,1]
	v_pk_add_f32 v[174:175], v[118:119], v[122:123]
	v_pk_add_f32 v[176:177], v[120:121], v[124:125]
	v_pk_mul_f32 v[178:179], v[118:119], v[118:119]
	v_pk_mul_f32 v[180:181], v[120:121], v[120:121]
	v_pk_fma_f32 v[178:179], v[122:123], v[122:123], v[178:179]
	v_pk_fma_f32 v[180:181], v[124:125], v[124:125], v[180:181]
	v_pk_add_f32 v[174:175], v[174:175], v[176:177]
	v_pk_add_f32 v[178:179], v[178:179], v[180:181]
	v_cvt_pk_bf16_f32 v208, v118, v119
	v_cvt_pk_bf16_f32 v209, v120, v121
	v_cvt_pk_bf16_f32 v210, v122, v123
	v_cvt_pk_bf16_f32 v211, v124, v125
	v_add_f32_e32 v4, v174, v175
	v_add_f32_e32 v186, v178, v179
	v_lshlrev_b32_e32 v174, 16, v212
	v_and_b32_e32 v175, 0xffff0000, v212
	v_lshlrev_b32_e32 v176, 16, v213
	v_and_b32_e32 v177, 0xffff0000, v213
	v_lshlrev_b32_e32 v178, 16, v214
	v_and_b32_e32 v179, 0xffff0000, v214
	v_lshlrev_b32_e32 v180, 16, v215
	v_and_b32_e32 v181, 0xffff0000, v215
	v_pk_add_f32 v[174:175], v[174:175], v[146:147] op_sel_hi:[1,0] neg_lo:[0,1] neg_hi:[0,1]
	v_pk_add_f32 v[176:177], v[176:177], v[146:147] op_sel_hi:[1,0] neg_lo:[0,1] neg_hi:[0,1]
	v_pk_add_f32 v[178:179], v[178:179], v[146:147] op_sel_hi:[1,0] neg_lo:[0,1] neg_hi:[0,1]
	v_pk_add_f32 v[180:181], v[180:181], v[146:147] op_sel_hi:[1,0] neg_lo:[0,1] neg_hi:[0,1]
	v_pk_mul_f32 v[174:175], v[146:147], v[174:175] op_sel:[1,0] op_sel_hi:[1,1]
	v_pk_mul_f32 v[176:177], v[146:147], v[176:177] op_sel:[1,0] op_sel_hi:[1,1]
	v_pk_mul_f32 v[178:179], v[146:147], v[178:179] op_sel:[1,0] op_sel_hi:[1,1]
	v_pk_mul_f32 v[180:181], v[146:147], v[180:181] op_sel:[1,0] op_sel_hi:[1,1]
	v_pk_fma_f32 v[174:175], v[150:151], v[174:175], v[158:159]
	v_pk_fma_f32 v[176:177], v[152:153], v[176:177], v[160:161]
	v_pk_fma_f32 v[178:179], v[154:155], v[178:179], v[162:163]
	v_pk_fma_f32 v[180:181], v[156:157], v[180:181], v[164:165]
	v_pk_fma_f32 v[110:111], v[174:175], s[76:77], v[110:111] op_sel_hi:[1,0,1]
	v_pk_fma_f32 v[112:113], v[176:177], s[76:77], v[112:113] op_sel_hi:[1,0,1]
	v_pk_fma_f32 v[114:115], v[178:179], s[76:77], v[114:115] op_sel_hi:[1,0,1]
	v_pk_fma_f32 v[116:117], v[180:181], s[76:77], v[116:117] op_sel_hi:[1,0,1]
	v_pk_add_f32 v[174:175], v[110:111], v[114:115]
	v_pk_add_f32 v[176:177], v[112:113], v[116:117]
	v_pk_mul_f32 v[178:179], v[110:111], v[110:111]
	v_pk_mul_f32 v[180:181], v[112:113], v[112:113]
	v_pk_fma_f32 v[178:179], v[114:115], v[114:115], v[178:179]
	v_pk_fma_f32 v[180:181], v[116:117], v[116:117], v[180:181]
	v_pk_add_f32 v[174:175], v[174:175], v[176:177]
	v_pk_add_f32 v[178:179], v[178:179], v[180:181]
	v_cvt_pk_bf16_f32 v212, v110, v111
	v_cvt_pk_bf16_f32 v213, v112, v113
	v_cvt_pk_bf16_f32 v214, v114, v115
	v_cvt_pk_bf16_f32 v215, v116, v117
	v_add_f32_e32 v5, v174, v175
	v_add_f32_e32 v187, v178, v179
	v_lshlrev_b32_e32 v174, 16, v216
	v_and_b32_e32 v175, 0xffff0000, v216
	v_lshlrev_b32_e32 v176, 16, v217
	v_and_b32_e32 v177, 0xffff0000, v217
	v_lshlrev_b32_e32 v178, 16, v218
	v_and_b32_e32 v179, 0xffff0000, v218
	v_lshlrev_b32_e32 v180, 16, v219
	v_and_b32_e32 v181, 0xffff0000, v219
	v_pk_add_f32 v[174:175], v[174:175], v[148:149] op_sel_hi:[1,0] neg_lo:[0,1] neg_hi:[0,1]
	v_pk_add_f32 v[176:177], v[176:177], v[148:149] op_sel_hi:[1,0] neg_lo:[0,1] neg_hi:[0,1]
	v_pk_add_f32 v[178:179], v[178:179], v[148:149] op_sel_hi:[1,0] neg_lo:[0,1] neg_hi:[0,1]
	v_pk_add_f32 v[180:181], v[180:181], v[148:149] op_sel_hi:[1,0] neg_lo:[0,1] neg_hi:[0,1]
	v_pk_mul_f32 v[174:175], v[148:149], v[174:175] op_sel:[1,0] op_sel_hi:[1,1]
	v_pk_mul_f32 v[176:177], v[148:149], v[176:177] op_sel:[1,0] op_sel_hi:[1,1]
	v_pk_mul_f32 v[178:179], v[148:149], v[178:179] op_sel:[1,0] op_sel_hi:[1,1]
	v_pk_mul_f32 v[180:181], v[148:149], v[180:181] op_sel:[1,0] op_sel_hi:[1,1]
	v_pk_fma_f32 v[174:175], v[150:151], v[174:175], v[158:159]
	v_pk_fma_f32 v[176:177], v[152:153], v[176:177], v[160:161]
	v_pk_fma_f32 v[178:179], v[154:155], v[178:179], v[162:163]
	v_pk_fma_f32 v[180:181], v[156:157], v[180:181], v[164:165]
	v_pk_fma_f32 v[102:103], v[174:175], s[76:77], v[102:103] op_sel_hi:[1,0,1]
	v_pk_fma_f32 v[104:105], v[176:177], s[76:77], v[104:105] op_sel_hi:[1,0,1]
	v_pk_fma_f32 v[106:107], v[178:179], s[76:77], v[106:107] op_sel_hi:[1,0,1]
	v_pk_fma_f32 v[108:109], v[180:181], s[76:77], v[108:109] op_sel_hi:[1,0,1]
	v_pk_add_f32 v[174:175], v[102:103], v[106:107]
	v_pk_add_f32 v[176:177], v[104:105], v[108:109]
	v_pk_mul_f32 v[178:179], v[102:103], v[102:103]
	v_pk_mul_f32 v[180:181], v[104:105], v[104:105]
	v_pk_fma_f32 v[178:179], v[106:107], v[106:107], v[178:179]
	v_pk_fma_f32 v[180:181], v[108:109], v[108:109], v[180:181]
	v_pk_add_f32 v[174:175], v[174:175], v[176:177]
	v_pk_add_f32 v[178:179], v[178:179], v[180:181]
	v_cvt_pk_bf16_f32 v216, v102, v103
	v_cvt_pk_bf16_f32 v217, v104, v105
	v_cvt_pk_bf16_f32 v218, v106, v107
	v_cvt_pk_bf16_f32 v219, v108, v109
	v_add_f32_e32 v139, v174, v175
	v_add_f32_e32 v197, v178, v179
	global_load_dwordx4 v[102:105], v135, s[16:17]
	global_load_dwordx4 v[106:109], v135, s[6:7]
	global_load_dwordx4 v[110:113], v135, s[8:9]
	global_load_dwordx4 v[114:117], v135, s[10:11]
	global_load_dwordx4 v[118:121], v135, s[16:17] offset:256
	global_load_dwordx4 v[122:125], v135, s[6:7] offset:256
	global_load_dwordx4 v[126:129], v135, s[8:9] offset:256
	global_load_dwordx4 v[130:133], v135, s[10:11] offset:256
	global_store_dwordx4 v134, v[204:207], s[16:17]
	global_store_dwordx4 v134, v[208:211], s[6:7]
	global_store_dwordx4 v134, v[212:215], s[8:9]
	global_store_dwordx4 v134, v[216:219], s[10:11]
	ds_read_b128 v[150:153], v137 offset:512
	ds_read_b128 v[154:157], v137 offset:528
	ds_read_b128 v[158:161], v137 offset:1536
	ds_read_b128 v[162:165], v137 offset:1552
	s_waitcnt lgkmcnt(0)
	s_waitcnt vmcnt(12)
	v_lshlrev_b32_e32 v174, 16, v222
	v_and_b32_e32 v175, 0xffff0000, v222
	v_lshlrev_b32_e32 v176, 16, v223
	v_and_b32_e32 v177, 0xffff0000, v223
	v_lshlrev_b32_e32 v178, 16, v224
	v_and_b32_e32 v179, 0xffff0000, v224
	v_lshlrev_b32_e32 v180, 16, v225
	v_and_b32_e32 v181, 0xffff0000, v225
	v_pk_add_f32 v[174:175], v[174:175], v[142:143] op_sel_hi:[1,0] neg_lo:[0,1] neg_hi:[0,1]
	v_pk_add_f32 v[176:177], v[176:177], v[142:143] op_sel_hi:[1,0] neg_lo:[0,1] neg_hi:[0,1]
	v_pk_add_f32 v[178:179], v[178:179], v[142:143] op_sel_hi:[1,0] neg_lo:[0,1] neg_hi:[0,1]
	v_pk_add_f32 v[180:181], v[180:181], v[142:143] op_sel_hi:[1,0] neg_lo:[0,1] neg_hi:[0,1]
	v_pk_mul_f32 v[174:175], v[142:143], v[174:175] op_sel:[1,0] op_sel_hi:[1,1]
	v_pk_mul_f32 v[176:177], v[142:143], v[176:177] op_sel:[1,0] op_sel_hi:[1,1]
	v_pk_mul_f32 v[178:179], v[142:143], v[178:179] op_sel:[1,0] op_sel_hi:[1,1]
	v_pk_mul_f32 v[180:181], v[142:143], v[180:181] op_sel:[1,0] op_sel_hi:[1,1]
	v_pk_fma_f32 v[174:175], v[150:151], v[174:175], v[158:159]
	v_pk_fma_f32 v[176:177], v[152:153], v[176:177], v[160:161]
	v_pk_fma_f32 v[178:179], v[154:155], v[178:179], v[162:163]
	v_pk_fma_f32 v[180:181], v[156:157], v[180:181], v[164:165]
	v_pk_fma_f32 v[94:95], v[174:175], s[76:77], v[94:95] op_sel_hi:[1,0,1]
	v_pk_fma_f32 v[96:97], v[176:177], s[76:77], v[96:97] op_sel_hi:[1,0,1]
	v_pk_fma_f32 v[98:99], v[178:179], s[76:77], v[98:99] op_sel_hi:[1,0,1]
	v_pk_fma_f32 v[100:101], v[180:181], s[76:77], v[100:101] op_sel_hi:[1,0,1]
	v_pk_add_f32 v[174:175], v[94:95], v[98:99]
	v_pk_add_f32 v[176:177], v[96:97], v[100:101]
	v_pk_mul_f32 v[178:179], v[94:95], v[94:95]
	v_pk_mul_f32 v[180:181], v[96:97], v[96:97]
	v_pk_fma_f32 v[178:179], v[98:99], v[98:99], v[178:179]
	v_pk_fma_f32 v[180:181], v[100:101], v[100:101], v[180:181]
	v_pk_add_f32 v[174:175], v[174:175], v[176:177]
	v_pk_add_f32 v[178:179], v[178:179], v[180:181]
	v_cvt_pk_bf16_f32 v222, v94, v95
	v_cvt_pk_bf16_f32 v223, v96, v97
	v_cvt_pk_bf16_f32 v224, v98, v99
	v_cvt_pk_bf16_f32 v225, v100, v101
	v_add_f32_e32 v174, v174, v175
	v_add_f32_e32 v178, v178, v179
	v_add_f32_e32 v2, v2, v174
	v_add_f32_e32 v140, v140, v178
	v_lshlrev_b32_e32 v174, 16, v182
	v_and_b32_e32 v175, 0xffff0000, v182
	v_lshlrev_b32_e32 v176, 16, v183
	v_and_b32_e32 v177, 0xffff0000, v183
	v_lshlrev_b32_e32 v178, 16, v184
	v_and_b32_e32 v179, 0xffff0000, v184
	v_lshlrev_b32_e32 v180, 16, v185
	v_and_b32_e32 v181, 0xffff0000, v185
	v_pk_add_f32 v[174:175], v[174:175], v[144:145] op_sel_hi:[1,0] neg_lo:[0,1] neg_hi:[0,1]
	v_pk_add_f32 v[176:177], v[176:177], v[144:145] op_sel_hi:[1,0] neg_lo:[0,1] neg_hi:[0,1]
	v_pk_add_f32 v[178:179], v[178:179], v[144:145] op_sel_hi:[1,0] neg_lo:[0,1] neg_hi:[0,1]
	v_pk_add_f32 v[180:181], v[180:181], v[144:145] op_sel_hi:[1,0] neg_lo:[0,1] neg_hi:[0,1]
	v_pk_mul_f32 v[174:175], v[144:145], v[174:175] op_sel:[1,0] op_sel_hi:[1,1]
	v_pk_mul_f32 v[176:177], v[144:145], v[176:177] op_sel:[1,0] op_sel_hi:[1,1]
	v_pk_mul_f32 v[178:179], v[144:145], v[178:179] op_sel:[1,0] op_sel_hi:[1,1]
	v_pk_mul_f32 v[180:181], v[144:145], v[180:181] op_sel:[1,0] op_sel_hi:[1,1]
	v_pk_fma_f32 v[174:175], v[150:151], v[174:175], v[158:159]
	v_pk_fma_f32 v[176:177], v[152:153], v[176:177], v[160:161]
	v_pk_fma_f32 v[178:179], v[154:155], v[178:179], v[162:163]
	v_pk_fma_f32 v[180:181], v[156:157], v[180:181], v[164:165]
	v_pk_fma_f32 v[86:87], v[174:175], s[76:77], v[86:87] op_sel_hi:[1,0,1]
	v_pk_fma_f32 v[88:89], v[176:177], s[76:77], v[88:89] op_sel_hi:[1,0,1]
	v_pk_fma_f32 v[90:91], v[178:179], s[76:77], v[90:91] op_sel_hi:[1,0,1]
	v_pk_fma_f32 v[92:93], v[180:181], s[76:77], v[92:93] op_sel_hi:[1,0,1]
	v_pk_add_f32 v[174:175], v[86:87], v[90:91]
	v_pk_add_f32 v[176:177], v[88:89], v[92:93]
	v_pk_mul_f32 v[178:179], v[86:87], v[86:87]
	v_pk_mul_f32 v[180:181], v[88:89], v[88:89]
	v_pk_fma_f32 v[178:179], v[90:91], v[90:91], v[178:179]
	v_pk_fma_f32 v[180:181], v[92:93], v[92:93], v[180:181]
	v_pk_add_f32 v[174:175], v[174:175], v[176:177]
	v_pk_add_f32 v[178:179], v[178:179], v[180:181]
	v_cvt_pk_bf16_f32 v182, v86, v87
	v_cvt_pk_bf16_f32 v183, v88, v89
	v_cvt_pk_bf16_f32 v184, v90, v91
	v_cvt_pk_bf16_f32 v185, v92, v93
	v_add_f32_e32 v174, v174, v175
	v_add_f32_e32 v178, v178, v179
	v_add_f32_e32 v4, v4, v174
	v_add_f32_e32 v186, v186, v178
	v_lshlrev_b32_e32 v174, 16, v166
	v_and_b32_e32 v175, 0xffff0000, v166
	v_lshlrev_b32_e32 v176, 16, v167
	v_and_b32_e32 v177, 0xffff0000, v167
	v_lshlrev_b32_e32 v178, 16, v168
	v_and_b32_e32 v179, 0xffff0000, v168
	v_lshlrev_b32_e32 v180, 16, v169
	v_and_b32_e32 v181, 0xffff0000, v169
	v_pk_add_f32 v[174:175], v[174:175], v[146:147] op_sel_hi:[1,0] neg_lo:[0,1] neg_hi:[0,1]
	v_pk_add_f32 v[176:177], v[176:177], v[146:147] op_sel_hi:[1,0] neg_lo:[0,1] neg_hi:[0,1]
	v_pk_add_f32 v[178:179], v[178:179], v[146:147] op_sel_hi:[1,0] neg_lo:[0,1] neg_hi:[0,1]
	v_pk_add_f32 v[180:181], v[180:181], v[146:147] op_sel_hi:[1,0] neg_lo:[0,1] neg_hi:[0,1]
	v_pk_mul_f32 v[174:175], v[146:147], v[174:175] op_sel:[1,0] op_sel_hi:[1,1]
	v_pk_mul_f32 v[176:177], v[146:147], v[176:177] op_sel:[1,0] op_sel_hi:[1,1]
	v_pk_mul_f32 v[178:179], v[146:147], v[178:179] op_sel:[1,0] op_sel_hi:[1,1]
	v_pk_mul_f32 v[180:181], v[146:147], v[180:181] op_sel:[1,0] op_sel_hi:[1,1]
	v_pk_fma_f32 v[174:175], v[150:151], v[174:175], v[158:159]
	v_pk_fma_f32 v[176:177], v[152:153], v[176:177], v[160:161]
	v_pk_fma_f32 v[178:179], v[154:155], v[178:179], v[162:163]
	v_pk_fma_f32 v[180:181], v[156:157], v[180:181], v[164:165]
	v_pk_fma_f32 v[78:79], v[174:175], s[76:77], v[78:79] op_sel_hi:[1,0,1]
	v_pk_fma_f32 v[80:81], v[176:177], s[76:77], v[80:81] op_sel_hi:[1,0,1]
	v_pk_fma_f32 v[82:83], v[178:179], s[76:77], v[82:83] op_sel_hi:[1,0,1]
	v_pk_fma_f32 v[84:85], v[180:181], s[76:77], v[84:85] op_sel_hi:[1,0,1]
	v_pk_add_f32 v[174:175], v[78:79], v[82:83]
	v_pk_add_f32 v[176:177], v[80:81], v[84:85]
	v_pk_mul_f32 v[178:179], v[78:79], v[78:79]
	v_pk_mul_f32 v[180:181], v[80:81], v[80:81]
	v_pk_fma_f32 v[178:179], v[82:83], v[82:83], v[178:179]
	v_pk_fma_f32 v[180:181], v[84:85], v[84:85], v[180:181]
	v_pk_add_f32 v[174:175], v[174:175], v[176:177]
	v_pk_add_f32 v[178:179], v[178:179], v[180:181]
	v_cvt_pk_bf16_f32 v166, v78, v79
	v_cvt_pk_bf16_f32 v167, v80, v81
	v_cvt_pk_bf16_f32 v168, v82, v83
	v_cvt_pk_bf16_f32 v169, v84, v85
	v_add_f32_e32 v174, v174, v175
	v_add_f32_e32 v178, v178, v179
	v_add_f32_e32 v5, v5, v174
	v_add_f32_e32 v187, v187, v178
	v_lshlrev_b32_e32 v174, 16, v170
	v_and_b32_e32 v175, 0xffff0000, v170
	v_lshlrev_b32_e32 v176, 16, v171
	v_and_b32_e32 v177, 0xffff0000, v171
	v_lshlrev_b32_e32 v178, 16, v172
	v_and_b32_e32 v179, 0xffff0000, v172
	v_lshlrev_b32_e32 v180, 16, v173
	v_and_b32_e32 v181, 0xffff0000, v173
	v_pk_add_f32 v[174:175], v[174:175], v[148:149] op_sel_hi:[1,0] neg_lo:[0,1] neg_hi:[0,1]
	v_pk_add_f32 v[176:177], v[176:177], v[148:149] op_sel_hi:[1,0] neg_lo:[0,1] neg_hi:[0,1]
	v_pk_add_f32 v[178:179], v[178:179], v[148:149] op_sel_hi:[1,0] neg_lo:[0,1] neg_hi:[0,1]
	v_pk_add_f32 v[180:181], v[180:181], v[148:149] op_sel_hi:[1,0] neg_lo:[0,1] neg_hi:[0,1]
	v_pk_mul_f32 v[174:175], v[148:149], v[174:175] op_sel:[1,0] op_sel_hi:[1,1]
	v_pk_mul_f32 v[176:177], v[148:149], v[176:177] op_sel:[1,0] op_sel_hi:[1,1]
	v_pk_mul_f32 v[178:179], v[148:149], v[178:179] op_sel:[1,0] op_sel_hi:[1,1]
	v_pk_mul_f32 v[180:181], v[148:149], v[180:181] op_sel:[1,0] op_sel_hi:[1,1]
	v_pk_fma_f32 v[174:175], v[150:151], v[174:175], v[158:159]
	v_pk_fma_f32 v[176:177], v[152:153], v[176:177], v[160:161]
	v_pk_fma_f32 v[178:179], v[154:155], v[178:179], v[162:163]
	v_pk_fma_f32 v[180:181], v[156:157], v[180:181], v[164:165]
	v_pk_fma_f32 v[70:71], v[174:175], s[76:77], v[70:71] op_sel_hi:[1,0,1]
	v_pk_fma_f32 v[72:73], v[176:177], s[76:77], v[72:73] op_sel_hi:[1,0,1]
	v_pk_fma_f32 v[74:75], v[178:179], s[76:77], v[74:75] op_sel_hi:[1,0,1]
	v_pk_fma_f32 v[76:77], v[180:181], s[76:77], v[76:77] op_sel_hi:[1,0,1]
	v_pk_add_f32 v[174:175], v[70:71], v[74:75]
	v_pk_add_f32 v[176:177], v[72:73], v[76:77]
	v_pk_mul_f32 v[178:179], v[70:71], v[70:71]
	v_pk_mul_f32 v[180:181], v[72:73], v[72:73]
	v_pk_fma_f32 v[178:179], v[74:75], v[74:75], v[178:179]
	v_pk_fma_f32 v[180:181], v[76:77], v[76:77], v[180:181]
	v_pk_add_f32 v[174:175], v[174:175], v[176:177]
	v_pk_add_f32 v[178:179], v[178:179], v[180:181]
	v_cvt_pk_bf16_f32 v170, v70, v71
	v_cvt_pk_bf16_f32 v171, v72, v73
	v_cvt_pk_bf16_f32 v172, v74, v75
	v_cvt_pk_bf16_f32 v173, v76, v77
	v_add_f32_e32 v174, v174, v175
	v_add_f32_e32 v178, v178, v179
	v_add_f32_e32 v139, v139, v174
	v_add_f32_e32 v197, v197, v178
	global_store_dwordx4 v134, v[222:225], s[16:17] offset:256
	global_store_dwordx4 v134, v[182:185], s[6:7] offset:256
	global_store_dwordx4 v134, v[166:169], s[8:9] offset:256
	global_store_dwordx4 v134, v[170:173], s[10:11] offset:256
	ds_bpermute_b32 v174, v201, v2
	ds_bpermute_b32 v175, v201, v4
	ds_bpermute_b32 v176, v201, v5
	ds_bpermute_b32 v177, v201, v139
	ds_bpermute_b32 v178, v201, v140
	ds_bpermute_b32 v179, v201, v186
	ds_bpermute_b32 v180, v201, v187
	ds_bpermute_b32 v181, v201, v197
	s_waitcnt lgkmcnt(0)
	v_add_f32_e32 v2, v2, v174
	v_add_f32_e32 v4, v4, v175
	v_add_f32_e32 v5, v5, v176
	v_add_f32_e32 v139, v139, v177
	v_add_f32_e32 v140, v140, v178
	v_add_f32_e32 v186, v186, v179
	v_add_f32_e32 v187, v187, v180
	v_add_f32_e32 v197, v197, v181
	ds_bpermute_b32 v174, v203, v2
	ds_bpermute_b32 v175, v203, v4
	ds_bpermute_b32 v176, v203, v5
	ds_bpermute_b32 v177, v203, v139
	ds_bpermute_b32 v178, v203, v140
	ds_bpermute_b32 v179, v203, v186
	ds_bpermute_b32 v180, v203, v187
	ds_bpermute_b32 v181, v203, v197
	s_waitcnt lgkmcnt(0)
	v_add_f32_e32 v2, v2, v174
	v_add_f32_e32 v4, v4, v175
	v_add_f32_e32 v5, v5, v176
	v_add_f32_e32 v139, v139, v177
	v_add_f32_e32 v140, v140, v178
	v_add_f32_e32 v186, v186, v179
	v_add_f32_e32 v187, v187, v180
	v_add_f32_e32 v197, v197, v181
	v_cmp_eq_u32_e32 vcc, 1, v191
	s_nop 1
	v_cndmask_b32_e32 v2, v2, v4, vcc
	v_cndmask_b32_e32 v140, v140, v186, vcc
	v_cmp_eq_u32_e32 vcc, 2, v191
	s_nop 1
	v_cndmask_b32_e32 v2, v2, v5, vcc
	v_cndmask_b32_e32 v140, v140, v187, vcc
	v_cmp_eq_u32_e32 vcc, 3, v191
	s_nop 1
	v_cndmask_b32_e32 v2, v2, v139, vcc
	v_cndmask_b32_e32 v140, v140, v197, vcc
	global_atomic_add_f32 v138, v2, s[14:15]
	global_atomic_add_f32 v138, v140, s[14:15] offset:4
	ds_read2_b64 v[142:145], v136 offset0:128 offset1:144
	ds_read2_b64 v[146:149], v136 offset0:160 offset1:176
	ds_read_b128 v[150:153], v137
	ds_read_b128 v[154:157], v137 offset:16
	ds_read_b128 v[158:161], v137 offset:1024
	ds_read_b128 v[162:165], v137 offset:1040
	s_waitcnt lgkmcnt(0)
	v_mul_f32_e32 v142, 0x3a000000, v142
	v_mul_f32_e32 v174, v142, v142
	v_fma_f32 v174, v143, s72, -v174
	v_add_f32_e32 v174, 0x3727c5ac, v174
	v_mul_f32_e32 v144, 0x3a000000, v144
	v_mul_f32_e32 v175, v144, v144
	v_fma_f32 v175, v145, s72, -v175
	v_add_f32_e32 v175, 0x3727c5ac, v175
	v_mul_f32_e32 v146, 0x3a000000, v146
	v_mul_f32_e32 v176, v146, v146
	v_fma_f32 v176, v147, s72, -v176
	v_add_f32_e32 v176, 0x3727c5ac, v176
	v_mul_f32_e32 v148, 0x3a000000, v148
	v_mul_f32_e32 v177, v148, v148
	v_fma_f32 v177, v149, s72, -v177
	v_add_f32_e32 v177, 0x3727c5ac, v177
	v_rsq_f32_e32 v143, v174
	v_rsq_f32_e32 v145, v175
	v_rsq_f32_e32 v147, v176
	v_rsq_f32_e32 v149, v177
	s_nop 0
	s_waitcnt vmcnt(14)
	v_lshlrev_b32_e32 v174, 16, v102
	v_and_b32_e32 v175, 0xffff0000, v102
	v_lshlrev_b32_e32 v176, 16, v103
	v_and_b32_e32 v177, 0xffff0000, v103
	v_lshlrev_b32_e32 v178, 16, v104
	v_and_b32_e32 v179, 0xffff0000, v104
	v_lshlrev_b32_e32 v180, 16, v105
	v_and_b32_e32 v181, 0xffff0000, v105
	v_pk_add_f32 v[174:175], v[174:175], v[142:143] op_sel_hi:[1,0] neg_lo:[0,1] neg_hi:[0,1]
	v_pk_add_f32 v[176:177], v[176:177], v[142:143] op_sel_hi:[1,0] neg_lo:[0,1] neg_hi:[0,1]
	v_pk_add_f32 v[178:179], v[178:179], v[142:143] op_sel_hi:[1,0] neg_lo:[0,1] neg_hi:[0,1]
	v_pk_add_f32 v[180:181], v[180:181], v[142:143] op_sel_hi:[1,0] neg_lo:[0,1] neg_hi:[0,1]
	v_pk_mul_f32 v[174:175], v[142:143], v[174:175] op_sel:[1,0] op_sel_hi:[1,1]
	v_pk_mul_f32 v[176:177], v[142:143], v[176:177] op_sel:[1,0] op_sel_hi:[1,1]
	v_pk_mul_f32 v[178:179], v[142:143], v[178:179] op_sel:[1,0] op_sel_hi:[1,1]
	v_pk_mul_f32 v[180:181], v[142:143], v[180:181] op_sel:[1,0] op_sel_hi:[1,1]
	v_pk_fma_f32 v[174:175], v[150:151], v[174:175], v[158:159]
	v_pk_fma_f32 v[176:177], v[152:153], v[176:177], v[160:161]
	v_pk_fma_f32 v[178:179], v[154:155], v[178:179], v[162:163]
	v_pk_fma_f32 v[180:181], v[156:157], v[180:181], v[164:165]
	v_pk_fma_f32 v[46:47], v[174:175], s[76:77], v[46:47] op_sel_hi:[1,0,1]
	v_pk_fma_f32 v[48:49], v[176:177], s[76:77], v[48:49] op_sel_hi:[1,0,1]
	v_pk_fma_f32 v[50:51], v[178:179], s[76:77], v[50:51] op_sel_hi:[1,0,1]
	v_pk_fma_f32 v[52:53], v[180:181], s[76:77], v[52:53] op_sel_hi:[1,0,1]
	v_pk_add_f32 v[174:175], v[46:47], v[50:51]
	v_pk_add_f32 v[176:177], v[48:49], v[52:53]
	v_pk_mul_f32 v[178:179], v[46:47], v[46:47]
	v_pk_mul_f32 v[180:181], v[48:49], v[48:49]
	v_pk_fma_f32 v[178:179], v[50:51], v[50:51], v[178:179]
	v_pk_fma_f32 v[180:181], v[52:53], v[52:53], v[180:181]
	v_pk_add_f32 v[174:175], v[174:175], v[176:177]
	v_pk_add_f32 v[178:179], v[178:179], v[180:181]
	v_cvt_pk_bf16_f32 v102, v46, v47
	v_cvt_pk_bf16_f32 v103, v48, v49
	v_cvt_pk_bf16_f32 v104, v50, v51
	v_cvt_pk_bf16_f32 v105, v52, v53
	v_add_f32_e32 v2, v174, v175
	v_add_f32_e32 v140, v178, v179
	v_lshlrev_b32_e32 v174, 16, v106
	v_and_b32_e32 v175, 0xffff0000, v106
	v_lshlrev_b32_e32 v176, 16, v107
	v_and_b32_e32 v177, 0xffff0000, v107
	v_lshlrev_b32_e32 v178, 16, v108
	v_and_b32_e32 v179, 0xffff0000, v108
	v_lshlrev_b32_e32 v180, 16, v109
	v_and_b32_e32 v181, 0xffff0000, v109
	v_pk_add_f32 v[174:175], v[174:175], v[144:145] op_sel_hi:[1,0] neg_lo:[0,1] neg_hi:[0,1]
	v_pk_add_f32 v[176:177], v[176:177], v[144:145] op_sel_hi:[1,0] neg_lo:[0,1] neg_hi:[0,1]
	v_pk_add_f32 v[178:179], v[178:179], v[144:145] op_sel_hi:[1,0] neg_lo:[0,1] neg_hi:[0,1]
	v_pk_add_f32 v[180:181], v[180:181], v[144:145] op_sel_hi:[1,0] neg_lo:[0,1] neg_hi:[0,1]
	v_pk_mul_f32 v[174:175], v[144:145], v[174:175] op_sel:[1,0] op_sel_hi:[1,1]
	v_pk_mul_f32 v[176:177], v[144:145], v[176:177] op_sel:[1,0] op_sel_hi:[1,1]
	v_pk_mul_f32 v[178:179], v[144:145], v[178:179] op_sel:[1,0] op_sel_hi:[1,1]
	v_pk_mul_f32 v[180:181], v[144:145], v[180:181] op_sel:[1,0] op_sel_hi:[1,1]
	v_pk_fma_f32 v[174:175], v[150:151], v[174:175], v[158:159]
	v_pk_fma_f32 v[176:177], v[152:153], v[176:177], v[160:161]
	v_pk_fma_f32 v[178:179], v[154:155], v[178:179], v[162:163]
	v_pk_fma_f32 v[180:181], v[156:157], v[180:181], v[164:165]
	v_pk_fma_f32 v[38:39], v[174:175], s[76:77], v[38:39] op_sel_hi:[1,0,1]
	v_pk_fma_f32 v[40:41], v[176:177], s[76:77], v[40:41] op_sel_hi:[1,0,1]
	v_pk_fma_f32 v[42:43], v[178:179], s[76:77], v[42:43] op_sel_hi:[1,0,1]
	v_pk_fma_f32 v[44:45], v[180:181], s[76:77], v[44:45] op_sel_hi:[1,0,1]
	v_pk_add_f32 v[174:175], v[38:39], v[42:43]
	v_pk_add_f32 v[176:177], v[40:41], v[44:45]
	v_pk_mul_f32 v[178:179], v[38:39], v[38:39]
	v_pk_mul_f32 v[180:181], v[40:41], v[40:41]
	v_pk_fma_f32 v[178:179], v[42:43], v[42:43], v[178:179]
	v_pk_fma_f32 v[180:181], v[44:45], v[44:45], v[180:181]
	v_pk_add_f32 v[174:175], v[174:175], v[176:177]
	v_pk_add_f32 v[178:179], v[178:179], v[180:181]
	v_cvt_pk_bf16_f32 v106, v38, v39
	v_cvt_pk_bf16_f32 v107, v40, v41
	v_cvt_pk_bf16_f32 v108, v42, v43
	v_cvt_pk_bf16_f32 v109, v44, v45
	v_add_f32_e32 v4, v174, v175
	v_add_f32_e32 v186, v178, v179
	v_lshlrev_b32_e32 v174, 16, v110
	v_and_b32_e32 v175, 0xffff0000, v110
	v_lshlrev_b32_e32 v176, 16, v111
	v_and_b32_e32 v177, 0xffff0000, v111
	v_lshlrev_b32_e32 v178, 16, v112
	v_and_b32_e32 v179, 0xffff0000, v112
	v_lshlrev_b32_e32 v180, 16, v113
	v_and_b32_e32 v181, 0xffff0000, v113
	v_pk_add_f32 v[174:175], v[174:175], v[146:147] op_sel_hi:[1,0] neg_lo:[0,1] neg_hi:[0,1]
	v_pk_add_f32 v[176:177], v[176:177], v[146:147] op_sel_hi:[1,0] neg_lo:[0,1] neg_hi:[0,1]
	v_pk_add_f32 v[178:179], v[178:179], v[146:147] op_sel_hi:[1,0] neg_lo:[0,1] neg_hi:[0,1]
	v_pk_add_f32 v[180:181], v[180:181], v[146:147] op_sel_hi:[1,0] neg_lo:[0,1] neg_hi:[0,1]
	v_pk_mul_f32 v[174:175], v[146:147], v[174:175] op_sel:[1,0] op_sel_hi:[1,1]
	v_pk_mul_f32 v[176:177], v[146:147], v[176:177] op_sel:[1,0] op_sel_hi:[1,1]
	v_pk_mul_f32 v[178:179], v[146:147], v[178:179] op_sel:[1,0] op_sel_hi:[1,1]
	v_pk_mul_f32 v[180:181], v[146:147], v[180:181] op_sel:[1,0] op_sel_hi:[1,1]
	v_pk_fma_f32 v[174:175], v[150:151], v[174:175], v[158:159]
	v_pk_fma_f32 v[176:177], v[152:153], v[176:177], v[160:161]
	v_pk_fma_f32 v[178:179], v[154:155], v[178:179], v[162:163]
	v_pk_fma_f32 v[180:181], v[156:157], v[180:181], v[164:165]
	v_pk_fma_f32 v[30:31], v[174:175], s[76:77], v[30:31] op_sel_hi:[1,0,1]
	v_pk_fma_f32 v[32:33], v[176:177], s[76:77], v[32:33] op_sel_hi:[1,0,1]
	v_pk_fma_f32 v[34:35], v[178:179], s[76:77], v[34:35] op_sel_hi:[1,0,1]
	v_pk_fma_f32 v[36:37], v[180:181], s[76:77], v[36:37] op_sel_hi:[1,0,1]
	v_pk_add_f32 v[174:175], v[30:31], v[34:35]
	v_pk_add_f32 v[176:177], v[32:33], v[36:37]
	v_pk_mul_f32 v[178:179], v[30:31], v[30:31]
	v_pk_mul_f32 v[180:181], v[32:33], v[32:33]
	v_pk_fma_f32 v[178:179], v[34:35], v[34:35], v[178:179]
	v_pk_fma_f32 v[180:181], v[36:37], v[36:37], v[180:181]
	v_pk_add_f32 v[174:175], v[174:175], v[176:177]
	v_pk_add_f32 v[178:179], v[178:179], v[180:181]
	v_cvt_pk_bf16_f32 v110, v30, v31
	v_cvt_pk_bf16_f32 v111, v32, v33
	v_cvt_pk_bf16_f32 v112, v34, v35
	v_cvt_pk_bf16_f32 v113, v36, v37
	v_add_f32_e32 v5, v174, v175
	v_add_f32_e32 v187, v178, v179
	v_lshlrev_b32_e32 v174, 16, v114
	v_and_b32_e32 v175, 0xffff0000, v114
	v_lshlrev_b32_e32 v176, 16, v115
	v_and_b32_e32 v177, 0xffff0000, v115
	v_lshlrev_b32_e32 v178, 16, v116
	v_and_b32_e32 v179, 0xffff0000, v116
	v_lshlrev_b32_e32 v180, 16, v117
	v_and_b32_e32 v181, 0xffff0000, v117
	v_pk_add_f32 v[174:175], v[174:175], v[148:149] op_sel_hi:[1,0] neg_lo:[0,1] neg_hi:[0,1]
	v_pk_add_f32 v[176:177], v[176:177], v[148:149] op_sel_hi:[1,0] neg_lo:[0,1] neg_hi:[0,1]
	v_pk_add_f32 v[178:179], v[178:179], v[148:149] op_sel_hi:[1,0] neg_lo:[0,1] neg_hi:[0,1]
	v_pk_add_f32 v[180:181], v[180:181], v[148:149] op_sel_hi:[1,0] neg_lo:[0,1] neg_hi:[0,1]
	v_pk_mul_f32 v[174:175], v[148:149], v[174:175] op_sel:[1,0] op_sel_hi:[1,1]
	v_pk_mul_f32 v[176:177], v[148:149], v[176:177] op_sel:[1,0] op_sel_hi:[1,1]
	v_pk_mul_f32 v[178:179], v[148:149], v[178:179] op_sel:[1,0] op_sel_hi:[1,1]
	v_pk_mul_f32 v[180:181], v[148:149], v[180:181] op_sel:[1,0] op_sel_hi:[1,1]
	v_pk_fma_f32 v[174:175], v[150:151], v[174:175], v[158:159]
	v_pk_fma_f32 v[176:177], v[152:153], v[176:177], v[160:161]
	v_pk_fma_f32 v[178:179], v[154:155], v[178:179], v[162:163]
	v_pk_fma_f32 v[180:181], v[156:157], v[180:181], v[164:165]
	v_pk_fma_f32 v[22:23], v[174:175], s[76:77], v[22:23] op_sel_hi:[1,0,1]
	v_pk_fma_f32 v[24:25], v[176:177], s[76:77], v[24:25] op_sel_hi:[1,0,1]
	v_pk_fma_f32 v[26:27], v[178:179], s[76:77], v[26:27] op_sel_hi:[1,0,1]
	v_pk_fma_f32 v[28:29], v[180:181], s[76:77], v[28:29] op_sel_hi:[1,0,1]
	v_pk_add_f32 v[174:175], v[22:23], v[26:27]
	v_pk_add_f32 v[176:177], v[24:25], v[28:29]
	v_pk_mul_f32 v[178:179], v[22:23], v[22:23]
	v_pk_mul_f32 v[180:181], v[24:25], v[24:25]
	v_pk_fma_f32 v[178:179], v[26:27], v[26:27], v[178:179]
	v_pk_fma_f32 v[180:181], v[28:29], v[28:29], v[180:181]
	v_pk_add_f32 v[174:175], v[174:175], v[176:177]
	v_pk_add_f32 v[178:179], v[178:179], v[180:181]
	v_cvt_pk_bf16_f32 v114, v22, v23
	v_cvt_pk_bf16_f32 v115, v24, v25
	v_cvt_pk_bf16_f32 v116, v26, v27
	v_cvt_pk_bf16_f32 v117, v28, v29
	v_add_f32_e32 v139, v174, v175
	v_add_f32_e32 v197, v178, v179
	global_store_dwordx4 v135, v[102:105], s[16:17]
	global_store_dwordx4 v135, v[106:109], s[6:7]
	global_store_dwordx4 v135, v[110:113], s[8:9]
	global_store_dwordx4 v135, v[114:117], s[10:11]
	ds_read_b128 v[150:153], v137 offset:512
	ds_read_b128 v[154:157], v137 offset:528
	ds_read_b128 v[158:161], v137 offset:1536
	ds_read_b128 v[162:165], v137 offset:1552
	s_waitcnt lgkmcnt(0)
	s_waitcnt vmcnt(14)
	v_lshlrev_b32_e32 v174, 16, v118
	v_and_b32_e32 v175, 0xffff0000, v118
	v_lshlrev_b32_e32 v176, 16, v119
	v_and_b32_e32 v177, 0xffff0000, v119
	v_lshlrev_b32_e32 v178, 16, v120
	v_and_b32_e32 v179, 0xffff0000, v120
	v_lshlrev_b32_e32 v180, 16, v121
	v_and_b32_e32 v181, 0xffff0000, v121
	v_pk_add_f32 v[174:175], v[174:175], v[142:143] op_sel_hi:[1,0] neg_lo:[0,1] neg_hi:[0,1]
	v_pk_add_f32 v[176:177], v[176:177], v[142:143] op_sel_hi:[1,0] neg_lo:[0,1] neg_hi:[0,1]
	v_pk_add_f32 v[178:179], v[178:179], v[142:143] op_sel_hi:[1,0] neg_lo:[0,1] neg_hi:[0,1]
	v_pk_add_f32 v[180:181], v[180:181], v[142:143] op_sel_hi:[1,0] neg_lo:[0,1] neg_hi:[0,1]
	v_pk_mul_f32 v[174:175], v[142:143], v[174:175] op_sel:[1,0] op_sel_hi:[1,1]
	v_pk_mul_f32 v[176:177], v[142:143], v[176:177] op_sel:[1,0] op_sel_hi:[1,1]
	v_pk_mul_f32 v[178:179], v[142:143], v[178:179] op_sel:[1,0] op_sel_hi:[1,1]
	v_pk_mul_f32 v[180:181], v[142:143], v[180:181] op_sel:[1,0] op_sel_hi:[1,1]
	v_pk_fma_f32 v[174:175], v[150:151], v[174:175], v[158:159]
	v_pk_fma_f32 v[176:177], v[152:153], v[176:177], v[160:161]
	v_pk_fma_f32 v[178:179], v[154:155], v[178:179], v[162:163]
	v_pk_fma_f32 v[180:181], v[156:157], v[180:181], v[164:165]
	v_pk_fma_f32 v[14:15], v[174:175], s[76:77], v[14:15] op_sel_hi:[1,0,1]
	v_pk_fma_f32 v[16:17], v[176:177], s[76:77], v[16:17] op_sel_hi:[1,0,1]
	v_pk_fma_f32 v[18:19], v[178:179], s[76:77], v[18:19] op_sel_hi:[1,0,1]
	v_pk_fma_f32 v[20:21], v[180:181], s[76:77], v[20:21] op_sel_hi:[1,0,1]
	v_pk_add_f32 v[174:175], v[14:15], v[18:19]
	v_pk_add_f32 v[176:177], v[16:17], v[20:21]
	v_pk_mul_f32 v[178:179], v[14:15], v[14:15]
	v_pk_mul_f32 v[180:181], v[16:17], v[16:17]
	v_pk_fma_f32 v[178:179], v[18:19], v[18:19], v[178:179]
	v_pk_fma_f32 v[180:181], v[20:21], v[20:21], v[180:181]
	v_pk_add_f32 v[174:175], v[174:175], v[176:177]
	v_pk_add_f32 v[178:179], v[178:179], v[180:181]
	v_cvt_pk_bf16_f32 v118, v14, v15
	v_cvt_pk_bf16_f32 v119, v16, v17
	v_cvt_pk_bf16_f32 v120, v18, v19
	v_cvt_pk_bf16_f32 v121, v20, v21
	v_add_f32_e32 v174, v174, v175
	v_add_f32_e32 v178, v178, v179
	v_add_f32_e32 v2, v2, v174
	v_add_f32_e32 v140, v140, v178
	v_lshlrev_b32_e32 v174, 16, v122
	v_and_b32_e32 v175, 0xffff0000, v122
	v_lshlrev_b32_e32 v176, 16, v123
	v_and_b32_e32 v177, 0xffff0000, v123
	v_lshlrev_b32_e32 v178, 16, v124
	v_and_b32_e32 v179, 0xffff0000, v124
	v_lshlrev_b32_e32 v180, 16, v125
	v_and_b32_e32 v181, 0xffff0000, v125
	v_pk_add_f32 v[174:175], v[174:175], v[144:145] op_sel_hi:[1,0] neg_lo:[0,1] neg_hi:[0,1]
	v_pk_add_f32 v[176:177], v[176:177], v[144:145] op_sel_hi:[1,0] neg_lo:[0,1] neg_hi:[0,1]
	v_pk_add_f32 v[178:179], v[178:179], v[144:145] op_sel_hi:[1,0] neg_lo:[0,1] neg_hi:[0,1]
	v_pk_add_f32 v[180:181], v[180:181], v[144:145] op_sel_hi:[1,0] neg_lo:[0,1] neg_hi:[0,1]
	v_pk_mul_f32 v[174:175], v[144:145], v[174:175] op_sel:[1,0] op_sel_hi:[1,1]
	v_pk_mul_f32 v[176:177], v[144:145], v[176:177] op_sel:[1,0] op_sel_hi:[1,1]
	v_pk_mul_f32 v[178:179], v[144:145], v[178:179] op_sel:[1,0] op_sel_hi:[1,1]
	v_pk_mul_f32 v[180:181], v[144:145], v[180:181] op_sel:[1,0] op_sel_hi:[1,1]
	v_pk_fma_f32 v[174:175], v[150:151], v[174:175], v[158:159]
	v_pk_fma_f32 v[176:177], v[152:153], v[176:177], v[160:161]
	v_pk_fma_f32 v[178:179], v[154:155], v[178:179], v[162:163]
	v_pk_fma_f32 v[180:181], v[156:157], v[180:181], v[164:165]
	v_pk_fma_f32 v[6:7], v[174:175], s[76:77], v[6:7] op_sel_hi:[1,0,1]
	v_pk_fma_f32 v[8:9], v[176:177], s[76:77], v[8:9] op_sel_hi:[1,0,1]
	v_pk_fma_f32 v[10:11], v[178:179], s[76:77], v[10:11] op_sel_hi:[1,0,1]
	v_pk_fma_f32 v[12:13], v[180:181], s[76:77], v[12:13] op_sel_hi:[1,0,1]
	v_pk_add_f32 v[174:175], v[6:7], v[10:11]
	v_pk_add_f32 v[176:177], v[8:9], v[12:13]
	v_pk_mul_f32 v[178:179], v[6:7], v[6:7]
	v_pk_mul_f32 v[180:181], v[8:9], v[8:9]
	v_pk_fma_f32 v[178:179], v[10:11], v[10:11], v[178:179]
	v_pk_fma_f32 v[180:181], v[12:13], v[12:13], v[180:181]
	v_pk_add_f32 v[174:175], v[174:175], v[176:177]
	v_pk_add_f32 v[178:179], v[178:179], v[180:181]
	v_cvt_pk_bf16_f32 v122, v6, v7
	v_cvt_pk_bf16_f32 v123, v8, v9
	v_cvt_pk_bf16_f32 v124, v10, v11
	v_cvt_pk_bf16_f32 v125, v12, v13
	v_add_f32_e32 v174, v174, v175
	v_add_f32_e32 v178, v178, v179
	v_add_f32_e32 v4, v4, v174
	v_add_f32_e32 v186, v186, v178
	v_lshlrev_b32_e32 v174, 16, v126
	v_and_b32_e32 v175, 0xffff0000, v126
	v_lshlrev_b32_e32 v176, 16, v127
	v_and_b32_e32 v177, 0xffff0000, v127
	v_lshlrev_b32_e32 v178, 16, v128
	v_and_b32_e32 v179, 0xffff0000, v128
	v_lshlrev_b32_e32 v180, 16, v129
	v_and_b32_e32 v181, 0xffff0000, v129
	v_pk_add_f32 v[174:175], v[174:175], v[146:147] op_sel_hi:[1,0] neg_lo:[0,1] neg_hi:[0,1]
	v_pk_add_f32 v[176:177], v[176:177], v[146:147] op_sel_hi:[1,0] neg_lo:[0,1] neg_hi:[0,1]
	v_pk_add_f32 v[178:179], v[178:179], v[146:147] op_sel_hi:[1,0] neg_lo:[0,1] neg_hi:[0,1]
	v_pk_add_f32 v[180:181], v[180:181], v[146:147] op_sel_hi:[1,0] neg_lo:[0,1] neg_hi:[0,1]
	v_pk_mul_f32 v[174:175], v[146:147], v[174:175] op_sel:[1,0] op_sel_hi:[1,1]
	v_pk_mul_f32 v[176:177], v[146:147], v[176:177] op_sel:[1,0] op_sel_hi:[1,1]
	v_pk_mul_f32 v[178:179], v[146:147], v[178:179] op_sel:[1,0] op_sel_hi:[1,1]
	v_pk_mul_f32 v[180:181], v[146:147], v[180:181] op_sel:[1,0] op_sel_hi:[1,1]
	v_pk_fma_f32 v[174:175], v[150:151], v[174:175], v[158:159]
	v_pk_fma_f32 v[176:177], v[152:153], v[176:177], v[160:161]
	v_pk_fma_f32 v[178:179], v[154:155], v[178:179], v[162:163]
	v_pk_fma_f32 v[180:181], v[156:157], v[180:181], v[164:165]
	v_pk_fma_f32 v[54:55], v[174:175], s[76:77], v[54:55] op_sel_hi:[1,0,1]
	v_pk_fma_f32 v[56:57], v[176:177], s[76:77], v[56:57] op_sel_hi:[1,0,1]
	v_pk_fma_f32 v[62:63], v[178:179], s[76:77], v[62:63] op_sel_hi:[1,0,1]
	v_pk_fma_f32 v[64:65], v[180:181], s[76:77], v[64:65] op_sel_hi:[1,0,1]
	v_pk_add_f32 v[174:175], v[54:55], v[62:63]
	v_pk_add_f32 v[176:177], v[56:57], v[64:65]
	v_pk_mul_f32 v[178:179], v[54:55], v[54:55]
	v_pk_mul_f32 v[180:181], v[56:57], v[56:57]
	v_pk_fma_f32 v[178:179], v[62:63], v[62:63], v[178:179]
	v_pk_fma_f32 v[180:181], v[64:65], v[64:65], v[180:181]
	v_pk_add_f32 v[174:175], v[174:175], v[176:177]
	v_pk_add_f32 v[178:179], v[178:179], v[180:181]
	v_cvt_pk_bf16_f32 v126, v54, v55
	v_cvt_pk_bf16_f32 v127, v56, v57
	v_cvt_pk_bf16_f32 v128, v62, v63
	v_cvt_pk_bf16_f32 v129, v64, v65
	v_add_f32_e32 v174, v174, v175
	v_add_f32_e32 v178, v178, v179
	v_add_f32_e32 v5, v5, v174
	v_add_f32_e32 v187, v187, v178
	v_lshlrev_b32_e32 v174, 16, v130
	v_and_b32_e32 v175, 0xffff0000, v130
	v_lshlrev_b32_e32 v176, 16, v131
	v_and_b32_e32 v177, 0xffff0000, v131
	v_lshlrev_b32_e32 v178, 16, v132
	v_and_b32_e32 v179, 0xffff0000, v132
	v_lshlrev_b32_e32 v180, 16, v133
	v_and_b32_e32 v181, 0xffff0000, v133
	v_pk_add_f32 v[174:175], v[174:175], v[148:149] op_sel_hi:[1,0] neg_lo:[0,1] neg_hi:[0,1]
	v_pk_add_f32 v[176:177], v[176:177], v[148:149] op_sel_hi:[1,0] neg_lo:[0,1] neg_hi:[0,1]
	v_pk_add_f32 v[178:179], v[178:179], v[148:149] op_sel_hi:[1,0] neg_lo:[0,1] neg_hi:[0,1]
	v_pk_add_f32 v[180:181], v[180:181], v[148:149] op_sel_hi:[1,0] neg_lo:[0,1] neg_hi:[0,1]
	v_pk_mul_f32 v[174:175], v[148:149], v[174:175] op_sel:[1,0] op_sel_hi:[1,1]
	v_pk_mul_f32 v[176:177], v[148:149], v[176:177] op_sel:[1,0] op_sel_hi:[1,1]
	v_pk_mul_f32 v[178:179], v[148:149], v[178:179] op_sel:[1,0] op_sel_hi:[1,1]
	v_pk_mul_f32 v[180:181], v[148:149], v[180:181] op_sel:[1,0] op_sel_hi:[1,1]
	v_pk_fma_f32 v[174:175], v[150:151], v[174:175], v[158:159]
	v_pk_fma_f32 v[176:177], v[152:153], v[176:177], v[160:161]
	v_pk_fma_f32 v[178:179], v[154:155], v[178:179], v[162:163]
	v_pk_fma_f32 v[180:181], v[156:157], v[180:181], v[164:165]
	v_pk_fma_f32 v[58:59], v[174:175], s[76:77], v[58:59] op_sel_hi:[1,0,1]
	v_pk_fma_f32 v[60:61], v[176:177], s[76:77], v[60:61] op_sel_hi:[1,0,1]
	v_pk_fma_f32 v[66:67], v[178:179], s[76:77], v[66:67] op_sel_hi:[1,0,1]
	v_pk_fma_f32 v[68:69], v[180:181], s[76:77], v[68:69] op_sel_hi:[1,0,1]
	v_pk_add_f32 v[174:175], v[58:59], v[66:67]
	v_pk_add_f32 v[176:177], v[60:61], v[68:69]
	v_pk_mul_f32 v[178:179], v[58:59], v[58:59]
	v_pk_mul_f32 v[180:181], v[60:61], v[60:61]
	v_pk_fma_f32 v[178:179], v[66:67], v[66:67], v[178:179]
	v_pk_fma_f32 v[180:181], v[68:69], v[68:69], v[180:181]
	v_pk_add_f32 v[174:175], v[174:175], v[176:177]
	v_pk_add_f32 v[178:179], v[178:179], v[180:181]
	v_cvt_pk_bf16_f32 v130, v58, v59
	v_cvt_pk_bf16_f32 v131, v60, v61
	v_cvt_pk_bf16_f32 v132, v66, v67
	v_cvt_pk_bf16_f32 v133, v68, v69
	v_add_f32_e32 v174, v174, v175
	v_add_f32_e32 v178, v178, v179
	v_add_f32_e32 v139, v139, v174
	v_add_f32_e32 v197, v197, v178
	global_store_dwordx4 v135, v[118:121], s[16:17] offset:256
	global_store_dwordx4 v135, v[122:125], s[6:7] offset:256
	global_store_dwordx4 v135, v[126:129], s[8:9] offset:256
	global_store_dwordx4 v135, v[130:133], s[10:11] offset:256
	ds_bpermute_b32 v174, v201, v2
	ds_bpermute_b32 v175, v201, v4
	ds_bpermute_b32 v176, v201, v5
	ds_bpermute_b32 v177, v201, v139
	ds_bpermute_b32 v178, v201, v140
	ds_bpermute_b32 v179, v201, v186
	ds_bpermute_b32 v180, v201, v187
	ds_bpermute_b32 v181, v201, v197
	s_waitcnt lgkmcnt(0)
	v_add_f32_e32 v2, v2, v174
	v_add_f32_e32 v4, v4, v175
	v_add_f32_e32 v5, v5, v176
	v_add_f32_e32 v139, v139, v177
	v_add_f32_e32 v140, v140, v178
	v_add_f32_e32 v186, v186, v179
	v_add_f32_e32 v187, v187, v180
	v_add_f32_e32 v197, v197, v181
	ds_bpermute_b32 v174, v203, v2
	ds_bpermute_b32 v175, v203, v4
	ds_bpermute_b32 v176, v203, v5
	ds_bpermute_b32 v177, v203, v139
	ds_bpermute_b32 v178, v203, v140
	ds_bpermute_b32 v179, v203, v186
	ds_bpermute_b32 v180, v203, v187
	ds_bpermute_b32 v181, v203, v197
	s_waitcnt lgkmcnt(0)
	v_add_f32_e32 v2, v2, v174
	v_add_f32_e32 v4, v4, v175
	v_add_f32_e32 v5, v5, v176
	v_add_f32_e32 v139, v139, v177
	v_add_f32_e32 v140, v140, v178
	v_add_f32_e32 v186, v186, v179
	v_add_f32_e32 v187, v187, v180
	v_add_f32_e32 v197, v197, v181
	v_cmp_eq_u32_e32 vcc, 1, v191
	s_nop 1
	v_cndmask_b32_e32 v2, v2, v4, vcc
	v_cndmask_b32_e32 v140, v140, v186, vcc
	v_cmp_eq_u32_e32 vcc, 2, v191
	s_nop 1
	v_cndmask_b32_e32 v2, v2, v5, vcc
	v_cndmask_b32_e32 v140, v140, v187, vcc
	v_cmp_eq_u32_e32 vcc, 3, v191
	s_nop 1
	v_cndmask_b32_e32 v2, v2, v139, vcc
	v_cndmask_b32_e32 v140, v140, v197, vcc
	global_atomic_add_f32 v138, v2, s[14:15] offset:1024
	global_atomic_add_f32 v138, v140, s[14:15] offset:1028
	s_branch .LBB0_1171
